# phase 0: scaled weight-conversion inner loop batched (8 weight + 8 scale loads in flight, one wait) instead of 8 serialized load/wait/mul/write steps
# baseline (speedup 1.0000x reference)
.LBB0_880:
	v_cndmask_b32_e64 v21, 0, 1, s[2:3]
	v_cmp_ne_u32_e64 s[0:1], 1, v21
	v_lshl_add_u64 v[106:107], v[32:33], 0, s[28:29]
	v_lshl_add_u64 v[108:109], v[48:49], 0, s[28:29]
	v_lshl_add_u64 v[110:111], v[46:47], 0, s[28:29]
	v_lshl_add_u64 v[112:113], v[44:45], 0, s[28:29]
	v_lshl_add_u64 v[114:115], v[42:43], 0, s[28:29]
	v_lshl_add_u64 v[116:117], v[40:41], 0, s[28:29]
	v_lshl_add_u64 v[118:119], v[34:35], 0, s[28:29]
	v_lshl_add_u64 v[120:121], v[30:31], 0, s[28:29]
	global_load_dword v122, v[106:107], off
	global_load_dword v123, v[108:109], off
	global_load_dword v124, v[110:111], off
	global_load_dword v125, v[112:113], off
	global_load_dword v126, v[114:115], off
	global_load_dword v127, v[116:117], off
	global_load_dword v128, v[118:119], off
	global_load_dword v129, v[120:121], off
	s_andn2_b64 vcc, exec, s[2:3]
	s_cbranch_vccnz .Lcv_noscale
	v_lshl_add_u64 v[50:51], s[40:41], 0, v[38:39]
	global_load_dword v130, v[50:51], off offset:-56
	global_load_dword v131, v[50:51], off offset:-48
	global_load_dword v132, v[50:51], off offset:-40
	global_load_dword v133, v[50:51], off offset:-32
	global_load_dword v134, v[50:51], off offset:-24
	global_load_dword v135, v[50:51], off offset:-16
	global_load_dword v136, v[50:51], off offset:-8
	global_load_dword v137, v[50:51], off
	s_waitcnt vmcnt(0)
	v_mul_f32_e32 v122, v122, v130
	v_mul_f32_e32 v123, v123, v131
	v_mul_f32_e32 v124, v124, v132
	v_mul_f32_e32 v125, v125, v133
	v_mul_f32_e32 v126, v126, v134
	v_mul_f32_e32 v127, v127, v135
	v_mul_f32_e32 v128, v128, v136
	v_mul_f32_e32 v129, v129, v137
.Lcv_noscale:
	s_waitcnt vmcnt(0)
	ds_write_b32 v1, v122
	ds_write_b32 v1, v123 offset:264
	ds_write_b32 v1, v124 offset:528
	ds_write_b32 v1, v125 offset:792
	ds_write_b32 v1, v126 offset:1056
	ds_write_b32 v1, v127 offset:1320
	ds_write_b32 v1, v128 offset:1584
	ds_write_b32 v1, v129 offset:1848
	s_add_u32 s28, s28, 0x10000
	s_addc_u32 s29, s29, 0
	s_add_u32 s40, s40, 64
	s_addc_u32 s41, s41, 0
	v_add_u32_e32 v1, 0x840, v1
	s_cmp_eq_u32 s28, 0x40000
	s_cbranch_scc0 .LBB0_880
	s_branch .LBB0_877
